# context-row w_out tiles (split-K finishers) use the fused epilogue too (ctx -> ctx1), post phase empty in fused mode, grid barrier between the w_out GEMM and post dropped at both layers
# baseline (speedup 1.0000x reference)
.Lgo_sk_wd:
	s_barrier
	global_load_dwordx4 v[194:197], v170, s[94:95] sc0 sc1
	global_load_dwordx4 v[198:201], v170, s[94:95] offset:1024 sc0 sc1
	global_load_dwordx4 v[202:205], v170, s[94:95] offset:2048 sc0 sc1
	global_load_dwordx4 v[206:209], v170, s[94:95] offset:3072 sc0 sc1
	v_add_u32_e32 v170, 0x1000, v170
	global_load_dwordx4 v[210:213], v170, s[94:95] sc0 sc1
	global_load_dwordx4 v[214:217], v170, s[94:95] offset:1024 sc0 sc1
	global_load_dwordx4 v[218:221], v170, s[94:95] offset:2048 sc0 sc1
	global_load_dwordx4 v[222:225], v170, s[94:95] offset:3072 sc0 sc1
	v_add_u32_e32 v170, 0x1000, v170
	global_load_dwordx4 v[226:229], v170, s[94:95] sc0 sc1
	global_load_dwordx4 v[230:233], v170, s[94:95] offset:1024 sc0 sc1
	global_load_dwordx4 v[234:237], v170, s[94:95] offset:2048 sc0 sc1
	global_load_dwordx4 v[238:241], v170, s[94:95] offset:3072 sc0 sc1
	v_add_u32_e32 v170, 0x1000, v170
	global_load_dwordx4 v[242:245], v170, s[94:95] sc0 sc1
	global_load_dwordx4 v[246:249], v170, s[94:95] offset:1024 sc0 sc1
	global_load_dwordx4 v[250:253], v170, s[94:95] offset:2048 sc0 sc1
	s_waitcnt vmcnt(7)
	v_pk_add_f32 v[0:1], v[0:1], v[194:195]
	v_pk_add_f32 v[2:3], v[2:3], v[196:197]
	v_pk_add_f32 v[4:5], v[4:5], v[198:199]
	v_pk_add_f32 v[6:7], v[6:7], v[200:201]
	v_pk_add_f32 v[8:9], v[8:9], v[202:203]
	v_pk_add_f32 v[10:11], v[10:11], v[204:205]
	v_pk_add_f32 v[12:13], v[12:13], v[206:207]
	v_pk_add_f32 v[14:15], v[14:15], v[208:209]
	v_pk_add_f32 v[16:17], v[16:17], v[210:211]
	v_pk_add_f32 v[18:19], v[18:19], v[212:213]
	v_pk_add_f32 v[20:21], v[20:21], v[214:215]
	v_pk_add_f32 v[22:23], v[22:23], v[216:217]
	v_pk_add_f32 v[24:25], v[24:25], v[218:219]
	v_pk_add_f32 v[26:27], v[26:27], v[220:221]
	v_pk_add_f32 v[28:29], v[28:29], v[222:223]
	v_pk_add_f32 v[30:31], v[30:31], v[224:225]
	global_load_dwordx4 v[194:197], v170, s[94:95] offset:3072 sc0 sc1
	v_add_u32_e32 v170, 0x1000, v170
	global_load_dwordx4 v[198:201], v170, s[94:95] sc0 sc1
	global_load_dwordx4 v[202:205], v170, s[94:95] offset:1024 sc0 sc1
	global_load_dwordx4 v[206:209], v170, s[94:95] offset:2048 sc0 sc1
	global_load_dwordx4 v[210:213], v170, s[94:95] offset:3072 sc0 sc1
	v_add_u32_e32 v170, 0x1000, v170
	global_load_dwordx4 v[214:217], v170, s[94:95] sc0 sc1
	global_load_dwordx4 v[218:221], v170, s[94:95] offset:1024 sc0 sc1
	global_load_dwordx4 v[222:225], v170, s[94:95] offset:2048 sc0 sc1
	s_waitcnt vmcnt(8)
	v_pk_add_f32 v[32:33], v[32:33], v[226:227]
	v_pk_add_f32 v[34:35], v[34:35], v[228:229]
	v_pk_add_f32 v[36:37], v[36:37], v[230:231]
	v_pk_add_f32 v[38:39], v[38:39], v[232:233]
	v_pk_add_f32 v[40:41], v[40:41], v[234:235]
	v_pk_add_f32 v[42:43], v[42:43], v[236:237]
	v_pk_add_f32 v[44:45], v[44:45], v[238:239]
	v_pk_add_f32 v[46:47], v[46:47], v[240:241]
	v_pk_add_f32 v[48:49], v[48:49], v[242:243]
	v_pk_add_f32 v[50:51], v[50:51], v[244:245]
	v_pk_add_f32 v[52:53], v[52:53], v[246:247]
	v_pk_add_f32 v[54:55], v[54:55], v[248:249]
	v_pk_add_f32 v[56:57], v[56:57], v[250:251]
	v_pk_add_f32 v[58:59], v[58:59], v[252:253]
	global_load_dwordx4 v[226:229], v170, s[94:95] offset:3072 sc0 sc1
	v_add_u32_e32 v170, 0x1000, v170
	global_load_dwordx4 v[230:233], v170, s[94:95] sc0 sc1
	global_load_dwordx4 v[234:237], v170, s[94:95] offset:1024 sc0 sc1
	global_load_dwordx4 v[238:241], v170, s[94:95] offset:2048 sc0 sc1
	global_load_dwordx4 v[242:245], v170, s[94:95] offset:3072 sc0 sc1
	v_add_u32_e32 v170, 0x1000, v170
	global_load_dwordx4 v[246:249], v170, s[94:95] sc0 sc1
	global_load_dwordx4 v[250:253], v170, s[94:95] offset:1024 sc0 sc1
	s_waitcnt vmcnt(7)
	v_pk_add_f32 v[60:61], v[60:61], v[194:195]
	v_pk_add_f32 v[62:63], v[62:63], v[196:197]
	v_pk_add_f32 v[64:65], v[64:65], v[198:199]
	v_pk_add_f32 v[66:67], v[66:67], v[200:201]
	v_pk_add_f32 v[68:69], v[68:69], v[202:203]
	v_pk_add_f32 v[70:71], v[70:71], v[204:205]
	v_pk_add_f32 v[72:73], v[72:73], v[206:207]
	v_pk_add_f32 v[74:75], v[74:75], v[208:209]
	v_pk_add_f32 v[76:77], v[76:77], v[210:211]
	v_pk_add_f32 v[78:79], v[78:79], v[212:213]
	v_pk_add_f32 v[80:81], v[80:81], v[214:215]
	v_pk_add_f32 v[82:83], v[82:83], v[216:217]
	v_pk_add_f32 v[84:85], v[84:85], v[218:219]
	v_pk_add_f32 v[86:87], v[86:87], v[220:221]
	v_pk_add_f32 v[88:89], v[88:89], v[222:223]
	v_pk_add_f32 v[90:91], v[90:91], v[224:225]
	global_load_dwordx4 v[194:197], v170, s[94:95] offset:2048 sc0 sc1
	global_load_dwordx4 v[198:201], v170, s[94:95] offset:3072 sc0 sc1
	v_add_u32_e32 v170, 0x1000, v170
	s_waitcnt vmcnt(2)
	v_pk_add_f32 v[92:93], v[92:93], v[226:227]
	v_pk_add_f32 v[94:95], v[94:95], v[228:229]
	v_pk_add_f32 v[96:97], v[96:97], v[230:231]
	v_pk_add_f32 v[98:99], v[98:99], v[232:233]
	v_pk_add_f32 v[100:101], v[100:101], v[234:235]
	v_pk_add_f32 v[102:103], v[102:103], v[236:237]
	v_pk_add_f32 v[104:105], v[104:105], v[238:239]
	v_pk_add_f32 v[106:107], v[106:107], v[240:241]
	v_pk_add_f32 v[108:109], v[108:109], v[242:243]
	v_pk_add_f32 v[110:111], v[110:111], v[244:245]
	v_pk_add_f32 v[112:113], v[112:113], v[246:247]
	v_pk_add_f32 v[114:115], v[114:115], v[248:249]
	v_pk_add_f32 v[116:117], v[116:117], v[250:251]
	v_pk_add_f32 v[118:119], v[118:119], v[252:253]
	s_waitcnt vmcnt(0)
	v_pk_add_f32 v[120:121], v[120:121], v[194:195]
	v_pk_add_f32 v[122:123], v[122:123], v[196:197]
	v_pk_add_f32 v[124:125], v[124:125], v[198:199]
	v_pk_add_f32 v[126:127], v[126:127], v[200:201]
	s_branch .Lgo_fz_epi

.Lgo_fz_epi:
	s_nop 7
	s_nop 7
	s_load_dwordx2 s[94:95], s[88:89], 0x168
	s_load_dwordx2 s[98:99], s[88:89], 0x170
	s_load_dwordx2 s[2:3], s[88:89], 0xc0
	v_and_b32_e32 v160, 15, v167
	v_bfe_u32 v161, v167, 4, 2
	v_bfe_u32 v162, v167, 6, 2
	v_lshrrev_b32_e32 v163, 8, v167
	v_lshlrev_b32_e32 v163, 6, v163
	v_lshl_add_u32 v163, v161, 2, v163
	v_lshl_add_u32 v164, v162, 5, v160
	v_readlane_b32 s32, v255, 0
	s_lshr_b32 s45, s36, 8
	s_lshl_b32 s48, s45, 3
	s_lshr_b32 s57, s34, 8
	s_add_u32 s48, s48, s57
	s_lshl_b32 s48, s48, 10
	s_lshr_b32 s57, s36, 12
	s_mul_i32 s0, s32, 5
	s_add_u32 s57, s57, s0
	s_mul_i32 s57, s57, 0x6000
	s_add_u32 s57, s57, 0x4000
	v_lshlrev_b32_e32 v237, 2, v164
	s_lshl_b32 vcc_lo, s34, 2
	v_add_u32_e32 v237, vcc_lo, v237
	s_cmpk_ge_u32 s36, 0x4000
	s_cselect_b32 s0, 0x4000, 0
	s_sub_u32 s0, s36, s0
	v_add_u32_e32 v168, s0, v163
	v_lshlrev_b32_e32 v168, 13, v168
	v_add_u32_e32 v168, v168, v237
	v_add_u32_e32 v169, 0x2000, v168
	v_add_u32_e32 v170, 0x4000, v168
	v_add_u32_e32 v171, 0x6000, v168
	s_lshl_b32 s0, s45, 2
	s_add_u32 s0, s0, 0x204
	v_mov_b32_e32 v234, s0
	s_lshl_b32 s0, s45, 13
	v_lshl_add_u32 v235, v167, 2, s0
	s_lshl_b32 s45, s32, 4
	s_add_u32 s45, s45, 8
	s_cmpk_ge_u32 s36, 0x4000
	s_movk_i32 vcc_lo, 0xc8
	s_cselect_b32 vcc_lo, 0x160, vcc_lo
	s_cselect_b32 vcc_hi, 0x10, 0x0
	s_load_dwordx2 s[36:37], s[88:89], vcc_lo
	s_load_dwordx2 s[34:35], s[88:89], 0xf0
	s_load_dwordx2 s[0:1], s[88:89], vcc_hi
	v_mul_f32_e32 v194, v124, v124
	v_fmac_f32_e32 v194, v120, v120
	v_fmac_f32_e32 v194, v100, v100
	v_fmac_f32_e32 v194, v96, v96
	v_mul_f32_e32 v195, v125, v125
	v_fmac_f32_e32 v195, v121, v121
	v_fmac_f32_e32 v195, v101, v101
	v_fmac_f32_e32 v195, v97, v97
	v_mul_f32_e32 v196, v126, v126
	v_fmac_f32_e32 v196, v122, v122
	v_fmac_f32_e32 v196, v102, v102
	v_fmac_f32_e32 v196, v98, v98
	v_mul_f32_e32 v197, v127, v127
	v_fmac_f32_e32 v197, v123, v123
	v_fmac_f32_e32 v197, v103, v103
	v_fmac_f32_e32 v197, v99, v99
	v_mul_f32_e32 v198, v116, v116
	v_fmac_f32_e32 v198, v112, v112
	v_fmac_f32_e32 v198, v92, v92
	v_fmac_f32_e32 v198, v88, v88
	v_mul_f32_e32 v199, v117, v117
	v_fmac_f32_e32 v199, v113, v113
	v_fmac_f32_e32 v199, v93, v93
	v_fmac_f32_e32 v199, v89, v89
	v_mul_f32_e32 v200, v118, v118
	v_fmac_f32_e32 v200, v114, v114
	v_fmac_f32_e32 v200, v94, v94
	v_fmac_f32_e32 v200, v90, v90
	v_mul_f32_e32 v201, v119, v119
	v_fmac_f32_e32 v201, v115, v115
	v_fmac_f32_e32 v201, v95, v95
	v_fmac_f32_e32 v201, v91, v91
	v_mul_f32_e32 v202, v108, v108
	v_fmac_f32_e32 v202, v104, v104
	v_fmac_f32_e32 v202, v80, v80
	v_fmac_f32_e32 v202, v72, v72
	v_mul_f32_e32 v203, v109, v109
	v_fmac_f32_e32 v203, v105, v105
	v_fmac_f32_e32 v203, v81, v81
	v_fmac_f32_e32 v203, v73, v73
	v_mul_f32_e32 v204, v110, v110
	v_fmac_f32_e32 v204, v106, v106
	v_fmac_f32_e32 v204, v82, v82
	v_fmac_f32_e32 v204, v74, v74
	v_mul_f32_e32 v205, v111, v111
	v_fmac_f32_e32 v205, v107, v107
	v_fmac_f32_e32 v205, v83, v83
	v_fmac_f32_e32 v205, v75, v75
	v_mul_f32_e32 v206, v84, v84
	v_fmac_f32_e32 v206, v76, v76
	v_fmac_f32_e32 v206, v68, v68
	v_fmac_f32_e32 v206, v64, v64
	v_mul_f32_e32 v207, v85, v85
	v_fmac_f32_e32 v207, v77, v77
	v_fmac_f32_e32 v207, v69, v69
	v_fmac_f32_e32 v207, v65, v65
	v_mul_f32_e32 v208, v86, v86
	v_fmac_f32_e32 v208, v78, v78
	v_fmac_f32_e32 v208, v70, v70
	v_fmac_f32_e32 v208, v66, v66
	v_mul_f32_e32 v209, v87, v87
	v_fmac_f32_e32 v209, v79, v79
	v_fmac_f32_e32 v209, v71, v71
	v_fmac_f32_e32 v209, v67, v67
	v_mul_f32_e32 v210, v60, v60
	v_fmac_f32_e32 v210, v56, v56
	v_fmac_f32_e32 v210, v32, v32
	v_fmac_f32_e32 v210, v24, v24
	v_mul_f32_e32 v211, v61, v61
	v_fmac_f32_e32 v211, v57, v57
	v_fmac_f32_e32 v211, v33, v33
	v_fmac_f32_e32 v211, v25, v25
	v_mul_f32_e32 v212, v62, v62
	v_fmac_f32_e32 v212, v58, v58
	v_fmac_f32_e32 v212, v34, v34
	v_fmac_f32_e32 v212, v26, v26
	v_mul_f32_e32 v213, v63, v63
	v_fmac_f32_e32 v213, v59, v59
	v_fmac_f32_e32 v213, v35, v35
	v_fmac_f32_e32 v213, v27, v27
	v_mul_f32_e32 v214, v52, v52
	v_fmac_f32_e32 v214, v48, v48
	v_fmac_f32_e32 v214, v20, v20
	v_fmac_f32_e32 v214, v16, v16
	v_mul_f32_e32 v215, v53, v53
	v_fmac_f32_e32 v215, v49, v49
	v_fmac_f32_e32 v215, v21, v21
	v_fmac_f32_e32 v215, v17, v17
	v_mul_f32_e32 v216, v54, v54
	v_fmac_f32_e32 v216, v50, v50
	v_fmac_f32_e32 v216, v22, v22
	v_fmac_f32_e32 v216, v18, v18
	v_mul_f32_e32 v217, v55, v55
	v_fmac_f32_e32 v217, v51, v51
	v_fmac_f32_e32 v217, v23, v23
	v_fmac_f32_e32 v217, v19, v19
	v_mul_f32_e32 v218, v44, v44
	v_fmac_f32_e32 v218, v40, v40
	v_fmac_f32_e32 v218, v12, v12
	v_fmac_f32_e32 v218, v8, v8
	v_mul_f32_e32 v219, v45, v45
	v_fmac_f32_e32 v219, v41, v41
	v_fmac_f32_e32 v219, v13, v13
	v_fmac_f32_e32 v219, v9, v9
	v_mul_f32_e32 v220, v46, v46
	v_fmac_f32_e32 v220, v42, v42
	v_fmac_f32_e32 v220, v14, v14
	v_fmac_f32_e32 v220, v10, v10
	v_mul_f32_e32 v221, v47, v47
	v_fmac_f32_e32 v221, v43, v43
	v_fmac_f32_e32 v221, v15, v15
	v_fmac_f32_e32 v221, v11, v11
	v_mul_f32_e32 v222, v36, v36
	v_fmac_f32_e32 v222, v28, v28
	v_fmac_f32_e32 v222, v4, v4
	v_fmac_f32_e32 v222, v0, v0
	v_mul_f32_e32 v223, v37, v37
	v_fmac_f32_e32 v223, v29, v29
	v_fmac_f32_e32 v223, v5, v5
	v_fmac_f32_e32 v223, v1, v1
	v_mul_f32_e32 v224, v38, v38
	v_fmac_f32_e32 v224, v30, v30
	v_fmac_f32_e32 v224, v6, v6
	v_fmac_f32_e32 v224, v2, v2
	v_mul_f32_e32 v225, v39, v39
	v_fmac_f32_e32 v225, v31, v31
	v_fmac_f32_e32 v225, v7, v7
	v_fmac_f32_e32 v225, v3, v3
	s_nop 1
	v_add_f32_dpp v194, v194, v194 row_ror:8 row_mask:0xf bank_mask:0xf
	v_add_f32_dpp v195, v195, v195 row_ror:8 row_mask:0xf bank_mask:0xf
	v_add_f32_dpp v196, v196, v196 row_ror:8 row_mask:0xf bank_mask:0xf
	v_add_f32_dpp v197, v197, v197 row_ror:8 row_mask:0xf bank_mask:0xf
	v_add_f32_dpp v198, v198, v198 row_ror:8 row_mask:0xf bank_mask:0xf
	v_add_f32_dpp v199, v199, v199 row_ror:8 row_mask:0xf bank_mask:0xf
	v_add_f32_dpp v200, v200, v200 row_ror:8 row_mask:0xf bank_mask:0xf
	v_add_f32_dpp v201, v201, v201 row_ror:8 row_mask:0xf bank_mask:0xf
	v_add_f32_dpp v202, v202, v202 row_ror:8 row_mask:0xf bank_mask:0xf
	v_add_f32_dpp v203, v203, v203 row_ror:8 row_mask:0xf bank_mask:0xf
	v_add_f32_dpp v204, v204, v204 row_ror:8 row_mask:0xf bank_mask:0xf
	v_add_f32_dpp v205, v205, v205 row_ror:8 row_mask:0xf bank_mask:0xf
	v_add_f32_dpp v206, v206, v206 row_ror:8 row_mask:0xf bank_mask:0xf
	v_add_f32_dpp v207, v207, v207 row_ror:8 row_mask:0xf bank_mask:0xf
	v_add_f32_dpp v208, v208, v208 row_ror:8 row_mask:0xf bank_mask:0xf
	v_add_f32_dpp v209, v209, v209 row_ror:8 row_mask:0xf bank_mask:0xf
	v_add_f32_dpp v210, v210, v210 row_ror:8 row_mask:0xf bank_mask:0xf
	v_add_f32_dpp v211, v211, v211 row_ror:8 row_mask:0xf bank_mask:0xf
	v_add_f32_dpp v212, v212, v212 row_ror:8 row_mask:0xf bank_mask:0xf
	v_add_f32_dpp v213, v213, v213 row_ror:8 row_mask:0xf bank_mask:0xf
	v_add_f32_dpp v214, v214, v214 row_ror:8 row_mask:0xf bank_mask:0xf
	v_add_f32_dpp v215, v215, v215 row_ror:8 row_mask:0xf bank_mask:0xf
	v_add_f32_dpp v216, v216, v216 row_ror:8 row_mask:0xf bank_mask:0xf
	v_add_f32_dpp v217, v217, v217 row_ror:8 row_mask:0xf bank_mask:0xf
	v_add_f32_dpp v218, v218, v218 row_ror:8 row_mask:0xf bank_mask:0xf
	v_add_f32_dpp v219, v219, v219 row_ror:8 row_mask:0xf bank_mask:0xf
	v_add_f32_dpp v220, v220, v220 row_ror:8 row_mask:0xf bank_mask:0xf
	v_add_f32_dpp v221, v221, v221 row_ror:8 row_mask:0xf bank_mask:0xf
	v_add_f32_dpp v222, v222, v222 row_ror:8 row_mask:0xf bank_mask:0xf
	v_add_f32_dpp v223, v223, v223 row_ror:8 row_mask:0xf bank_mask:0xf
	v_add_f32_dpp v224, v224, v224 row_ror:8 row_mask:0xf bank_mask:0xf
	v_add_f32_dpp v225, v225, v225 row_ror:8 row_mask:0xf bank_mask:0xf
	s_nop 1
	v_add_f32_dpp v194, v194, v194 row_ror:4 row_mask:0xf bank_mask:0xf
	v_add_f32_dpp v195, v195, v195 row_ror:4 row_mask:0xf bank_mask:0xf
	v_add_f32_dpp v196, v196, v196 row_ror:4 row_mask:0xf bank_mask:0xf
	v_add_f32_dpp v197, v197, v197 row_ror:4 row_mask:0xf bank_mask:0xf
	v_add_f32_dpp v198, v198, v198 row_ror:4 row_mask:0xf bank_mask:0xf
	v_add_f32_dpp v199, v199, v199 row_ror:4 row_mask:0xf bank_mask:0xf
	v_add_f32_dpp v200, v200, v200 row_ror:4 row_mask:0xf bank_mask:0xf
	v_add_f32_dpp v201, v201, v201 row_ror:4 row_mask:0xf bank_mask:0xf
	v_add_f32_dpp v202, v202, v202 row_ror:4 row_mask:0xf bank_mask:0xf
	v_add_f32_dpp v203, v203, v203 row_ror:4 row_mask:0xf bank_mask:0xf
	v_add_f32_dpp v204, v204, v204 row_ror:4 row_mask:0xf bank_mask:0xf
	v_add_f32_dpp v205, v205, v205 row_ror:4 row_mask:0xf bank_mask:0xf
	v_add_f32_dpp v206, v206, v206 row_ror:4 row_mask:0xf bank_mask:0xf
	v_add_f32_dpp v207, v207, v207 row_ror:4 row_mask:0xf bank_mask:0xf
	v_add_f32_dpp v208, v208, v208 row_ror:4 row_mask:0xf bank_mask:0xf
	v_add_f32_dpp v209, v209, v209 row_ror:4 row_mask:0xf bank_mask:0xf
	v_add_f32_dpp v210, v210, v210 row_ror:4 row_mask:0xf bank_mask:0xf
	v_add_f32_dpp v211, v211, v211 row_ror:4 row_mask:0xf bank_mask:0xf
	v_add_f32_dpp v212, v212, v212 row_ror:4 row_mask:0xf bank_mask:0xf
	v_add_f32_dpp v213, v213, v213 row_ror:4 row_mask:0xf bank_mask:0xf
	v_add_f32_dpp v214, v214, v214 row_ror:4 row_mask:0xf bank_mask:0xf
	v_add_f32_dpp v215, v215, v215 row_ror:4 row_mask:0xf bank_mask:0xf
	v_add_f32_dpp v216, v216, v216 row_ror:4 row_mask:0xf bank_mask:0xf
	v_add_f32_dpp v217, v217, v217 row_ror:4 row_mask:0xf bank_mask:0xf
	v_add_f32_dpp v218, v218, v218 row_ror:4 row_mask:0xf bank_mask:0xf
	v_add_f32_dpp v219, v219, v219 row_ror:4 row_mask:0xf bank_mask:0xf
	v_add_f32_dpp v220, v220, v220 row_ror:4 row_mask:0xf bank_mask:0xf
	v_add_f32_dpp v221, v221, v221 row_ror:4 row_mask:0xf bank_mask:0xf
	v_add_f32_dpp v222, v222, v222 row_ror:4 row_mask:0xf bank_mask:0xf
	v_add_f32_dpp v223, v223, v223 row_ror:4 row_mask:0xf bank_mask:0xf
	v_add_f32_dpp v224, v224, v224 row_ror:4 row_mask:0xf bank_mask:0xf
	v_add_f32_dpp v225, v225, v225 row_ror:4 row_mask:0xf bank_mask:0xf
	s_nop 1
	v_add_f32_dpp v194, v194, v194 row_ror:2 row_mask:0xf bank_mask:0xf
	v_add_f32_dpp v195, v195, v195 row_ror:2 row_mask:0xf bank_mask:0xf
	v_add_f32_dpp v196, v196, v196 row_ror:2 row_mask:0xf bank_mask:0xf
	v_add_f32_dpp v197, v197, v197 row_ror:2 row_mask:0xf bank_mask:0xf
	v_add_f32_dpp v198, v198, v198 row_ror:2 row_mask:0xf bank_mask:0xf
	v_add_f32_dpp v199, v199, v199 row_ror:2 row_mask:0xf bank_mask:0xf
	v_add_f32_dpp v200, v200, v200 row_ror:2 row_mask:0xf bank_mask:0xf
	v_add_f32_dpp v201, v201, v201 row_ror:2 row_mask:0xf bank_mask:0xf
	v_add_f32_dpp v202, v202, v202 row_ror:2 row_mask:0xf bank_mask:0xf
	v_add_f32_dpp v203, v203, v203 row_ror:2 row_mask:0xf bank_mask:0xf
	v_add_f32_dpp v204, v204, v204 row_ror:2 row_mask:0xf bank_mask:0xf
	v_add_f32_dpp v205, v205, v205 row_ror:2 row_mask:0xf bank_mask:0xf
	v_add_f32_dpp v206, v206, v206 row_ror:2 row_mask:0xf bank_mask:0xf
	v_add_f32_dpp v207, v207, v207 row_ror:2 row_mask:0xf bank_mask:0xf
	v_add_f32_dpp v208, v208, v208 row_ror:2 row_mask:0xf bank_mask:0xf
	v_add_f32_dpp v209, v209, v209 row_ror:2 row_mask:0xf bank_mask:0xf
	v_add_f32_dpp v210, v210, v210 row_ror:2 row_mask:0xf bank_mask:0xf
	v_add_f32_dpp v211, v211, v211 row_ror:2 row_mask:0xf bank_mask:0xf
	v_add_f32_dpp v212, v212, v212 row_ror:2 row_mask:0xf bank_mask:0xf
	v_add_f32_dpp v213, v213, v213 row_ror:2 row_mask:0xf bank_mask:0xf
	v_add_f32_dpp v214, v214, v214 row_ror:2 row_mask:0xf bank_mask:0xf
	v_add_f32_dpp v215, v215, v215 row_ror:2 row_mask:0xf bank_mask:0xf
	v_add_f32_dpp v216, v216, v216 row_ror:2 row_mask:0xf bank_mask:0xf
	v_add_f32_dpp v217, v217, v217 row_ror:2 row_mask:0xf bank_mask:0xf
	v_add_f32_dpp v218, v218, v218 row_ror:2 row_mask:0xf bank_mask:0xf
	v_add_f32_dpp v219, v219, v219 row_ror:2 row_mask:0xf bank_mask:0xf
	v_add_f32_dpp v220, v220, v220 row_ror:2 row_mask:0xf bank_mask:0xf
	v_add_f32_dpp v221, v221, v221 row_ror:2 row_mask:0xf bank_mask:0xf
	v_add_f32_dpp v222, v222, v222 row_ror:2 row_mask:0xf bank_mask:0xf
	v_add_f32_dpp v223, v223, v223 row_ror:2 row_mask:0xf bank_mask:0xf
	v_add_f32_dpp v224, v224, v224 row_ror:2 row_mask:0xf bank_mask:0xf
	v_add_f32_dpp v225, v225, v225 row_ror:2 row_mask:0xf bank_mask:0xf
	s_nop 1
	v_add_f32_dpp v194, v194, v194 row_ror:1 row_mask:0xf bank_mask:0xf
	v_add_f32_dpp v195, v195, v195 row_ror:1 row_mask:0xf bank_mask:0xf
	v_add_f32_dpp v196, v196, v196 row_ror:1 row_mask:0xf bank_mask:0xf
	v_add_f32_dpp v197, v197, v197 row_ror:1 row_mask:0xf bank_mask:0xf
	v_add_f32_dpp v198, v198, v198 row_ror:1 row_mask:0xf bank_mask:0xf
	v_add_f32_dpp v199, v199, v199 row_ror:1 row_mask:0xf bank_mask:0xf
	v_add_f32_dpp v200, v200, v200 row_ror:1 row_mask:0xf bank_mask:0xf
	v_add_f32_dpp v201, v201, v201 row_ror:1 row_mask:0xf bank_mask:0xf
	v_add_f32_dpp v202, v202, v202 row_ror:1 row_mask:0xf bank_mask:0xf
	v_add_f32_dpp v203, v203, v203 row_ror:1 row_mask:0xf bank_mask:0xf
	v_add_f32_dpp v204, v204, v204 row_ror:1 row_mask:0xf bank_mask:0xf
	v_add_f32_dpp v205, v205, v205 row_ror:1 row_mask:0xf bank_mask:0xf
	v_add_f32_dpp v206, v206, v206 row_ror:1 row_mask:0xf bank_mask:0xf
	v_add_f32_dpp v207, v207, v207 row_ror:1 row_mask:0xf bank_mask:0xf
	v_add_f32_dpp v208, v208, v208 row_ror:1 row_mask:0xf bank_mask:0xf
	v_add_f32_dpp v209, v209, v209 row_ror:1 row_mask:0xf bank_mask:0xf
	v_add_f32_dpp v210, v210, v210 row_ror:1 row_mask:0xf bank_mask:0xf
	v_add_f32_dpp v211, v211, v211 row_ror:1 row_mask:0xf bank_mask:0xf
	v_add_f32_dpp v212, v212, v212 row_ror:1 row_mask:0xf bank_mask:0xf
	v_add_f32_dpp v213, v213, v213 row_ror:1 row_mask:0xf bank_mask:0xf
	v_add_f32_dpp v214, v214, v214 row_ror:1 row_mask:0xf bank_mask:0xf
	v_add_f32_dpp v215, v215, v215 row_ror:1 row_mask:0xf bank_mask:0xf
	v_add_f32_dpp v216, v216, v216 row_ror:1 row_mask:0xf bank_mask:0xf
	v_add_f32_dpp v217, v217, v217 row_ror:1 row_mask:0xf bank_mask:0xf
	v_add_f32_dpp v218, v218, v218 row_ror:1 row_mask:0xf bank_mask:0xf
	v_add_f32_dpp v219, v219, v219 row_ror:1 row_mask:0xf bank_mask:0xf
	v_add_f32_dpp v220, v220, v220 row_ror:1 row_mask:0xf bank_mask:0xf
	v_add_f32_dpp v221, v221, v221 row_ror:1 row_mask:0xf bank_mask:0xf
	v_add_f32_dpp v222, v222, v222 row_ror:1 row_mask:0xf bank_mask:0xf
	v_add_f32_dpp v223, v223, v223 row_ror:1 row_mask:0xf bank_mask:0xf
	v_add_f32_dpp v224, v224, v224 row_ror:1 row_mask:0xf bank_mask:0xf
	v_add_f32_dpp v225, v225, v225 row_ror:1 row_mask:0xf bank_mask:0xf
	v_lshlrev_b32_e32 v236, 10, v162
	v_lshl_add_u32 v236, v163, 2, v236
	v_add_u32_e32 v236, 0x20000, v236
	v_cmp_eq_u32_e32 vcc, 0, v160
	s_mov_b64 exec, vcc
	ds_write_b128 v236, v[194:197]
	ds_write_b128 v236, v[198:201] offset:64
	ds_write_b128 v236, v[202:205] offset:128
	ds_write_b128 v236, v[206:209] offset:192
	ds_write_b128 v236, v[210:213] offset:512
	ds_write_b128 v236, v[214:217] offset:576
	ds_write_b128 v236, v[218:221] offset:640
	ds_write_b128 v236, v[222:225] offset:704
	s_mov_b64 exec, -1
	s_waitcnt lgkmcnt(0)
	s_add_u32 s34, s34, s57
	s_addc_u32 s35, s35, 0
	s_lshl_b32 s57, s32, 13
	s_add_u32 s2, s2, s57
	s_addc_u32 s3, s3, 0
	s_cmp_eq_u32 s32, 0
	s_cselect_b32 s0, s0, s36
	s_cselect_b32 s1, s1, s37
	s_add_u32 s94, s94, 0x1000000
	s_addc_u32 s95, s95, 0
	v_readfirstlane_b32 s32, v167
	s_barrier
	s_cmp_lt_u32 s32, 0x100
	s_cbranch_scc0 .Lgo_fz_w1
	v_lshlrev_b32_e32 v238, 2, v167
	v_add_u32_e32 v239, 0x20000, v238
	ds_read_b32 v240, v239
	ds_read_b32 v241, v239 offset:1024
	ds_read_b32 v242, v239 offset:2048
	ds_read_b32 v243, v239 offset:3072
	v_add_u32_e32 v244, s48, v238
	s_waitcnt lgkmcnt(0)
	v_add_f32_e32 v240, v240, v241
	v_add_f32_e32 v240, v240, v242
	v_add_f32_e32 v240, v240, v243
	global_store_dword v244, v240, s[94:95] sc0 sc1
	s_waitcnt vmcnt(0)

.LBB0_1226:
	s_mov_b64 s[0:1], s[88:89]
	s_getreg_b32 s8, hwreg(HW_REG_XCC_ID, 0, 4)
	s_waitcnt vmcnt(0)
	s_waitcnt lgkmcnt(0)
	s_barrier
	s_mov_b64 s[10:11], exec
	v_readlane_b32 s23, v254, 1
	s_cmpk_eq_u32 s23, 0x100
	s_cbranch_scc1 .LBB0_1162
	v_readlane_b32 s22, v254, 5
	v_readlane_b32 s23, v254, 6
	s_and_b64 s[22:23], s[10:11], s[22:23]
	s_mov_b64 exec, s[22:23]
	s_cbranch_execz .LBB0_1162
	buffer_inv sc1
	s_load_dwordx2 s[22:23], s[0:1], 0x170
	v_readlane_b32 s24, v254, 45
	v_readlane_b32 s25, v254, 46
	s_and_b32 s8, s8, 15
	v_mov_b32_e32 v0, s24
	v_mov_b32_e32 v1, s25
	ds_read_b32 v2, v0
	ds_read_b32 v3, v1
	s_lshl_b32 s9, s8, 8
	v_mov_b32_e32 v4, 0x1400
	v_mov_b32_e32 v5, 1
	s_waitcnt lgkmcnt(0)
	s_add_u32 s24, s22, s9
	s_addc_u32 s25, s23, 0
	global_atomic_add v6, v4, v5, s[24:25] sc0
	v_cvt_f32_u32_e32 v7, v2
	v_rcp_f32_e32 v7, v7
	s_waitcnt vmcnt(0)
	v_cvt_f32_u32_e32 v8, v6
	v_add_f32_e32 v8, 0.5, v8
	v_mul_f32_e32 v8, v8, v7
	v_cvt_u32_f32_e32 v8, v8
	v_mul_lo_u32 v9, v8, v2
	v_sub_u32_e32 v9, v6, v9
	v_add_u32_e32 v9, 1, v9
	v_cmp_eq_u32_e32 vcc, v9, v2
	v_readfirstlane_b32 s26, v8
	s_cbranch_vccz .Lhb4_follow
	buffer_wbl2 sc1
	s_waitcnt vmcnt(0)
	v_mov_b32_e32 v4, 0x3400
	global_atomic_add v4, v5, s[22:23]
	v_readfirstlane_b32 s27, v3
	s_add_u32 s34, s26, 1
	s_mul_i32 s27, s34, s27
	s_mov_b32 s35, 0

.LBB0_1277:
.Lpost_entry:
	v_readlane_b32 s40, v255, 0
	v_readlane_b32 s9, v254, 1
	s_cmpk_eq_u32 s9, 0x100
	s_cbranch_scc1 .Lpost_done
	s_load_dwordx2 s[22:23], s[88:89], 0x0
	s_load_dwordx2 s[24:25], s[88:89], 0x10
	s_load_dwordx2 s[0:1], s[88:89], 0x30
	s_load_dwordx4 s[12:15], s[88:89], 0xc0
	s_load_dwordx2 s[26:27], s[88:89], 0xf0
	s_load_dwordx2 s[36:37], s[88:89], 0x110
	s_load_dwordx2 s[38:39], s[88:89], 0x130
	s_load_dwordx2 s[34:35], s[88:89], 0x160
	v_readlane_b32 s40, v255, 0
	v_readfirstlane_b32 s16, v167
	v_readlane_b32 s8, v254, 0
	v_readlane_b32 s9, v254, 1
	s_lshr_b32 s10, s16, 8
	s_mul_i32 s10, s10, s9
	s_add_u32 s10, s10, s8
	s_lshl_b32 s10, s10, 2
	s_bfe_u32 s16, s16, 0x20006
	s_add_u32 s16, s16, s10
	v_and_b32_e32 v228, 63, v167
	v_lshlrev_b32_e32 v226, 4, v228
	v_add_u32_e32 v227, 0x1000, v226
	v_lshlrev_b32_e32 v228, 3, v228
	s_waitcnt lgkmcnt(0)
	s_lshl_b32 s10, s40, 13
	s_add_u32 s12, s12, s10
	s_addc_u32 s13, s13, 0
	s_add_u32 s0, s0, 0x2000
	s_addc_u32 s1, s1, 0
	global_load_dwordx4 v[96:99], v226, s[12:13]
	global_load_dwordx4 v[100:103], v226, s[12:13] offset:1024
	global_load_dwordx4 v[104:107], v226, s[12:13] offset:2048
	global_load_dwordx4 v[108:111], v226, s[12:13] offset:3072
	global_load_dwordx4 v[112:115], v227, s[12:13]
	global_load_dwordx4 v[116:119], v227, s[12:13] offset:1024
	global_load_dwordx4 v[120:123], v227, s[12:13] offset:2048
	global_load_dwordx4 v[124:127], v227, s[12:13] offset:3072
	s_cmp_eq_u32 s40, 0
	s_cbranch_scc0 .Lpost_nopre
	global_load_dwordx4 v[194:197], v226, s[0:1]
	global_load_dwordx4 v[198:201], v226, s[0:1] offset:1024
	global_load_dwordx4 v[202:205], v226, s[0:1] offset:2048
	global_load_dwordx4 v[206:209], v226, s[0:1] offset:3072
	global_load_dwordx4 v[210:213], v227, s[0:1]
	global_load_dwordx4 v[214:217], v227, s[0:1] offset:1024
	global_load_dwordx4 v[218:221], v227, s[0:1] offset:2048
	global_load_dwordx4 v[222:225], v227, s[0:1] offset:3072
